# SwiGLU epilogues: all sigmoid +1.0 adds and most -log2e scalings fused into packed f32 ops (58 fewer VALU per epilogue)
# baseline (speedup 1.0000x reference)
.LBB0_438:
	v_pk_mul_f32 v[166:167], v[124:125], v[244:245] op_sel_hi:[1,0]
	v_exp_f32_e32 v166, v166
	v_exp_f32_e32 v167, v167
	s_ashr_i32 s91, s90, 31
	v_pk_add_f32 v[166:167], v[166:167], 1.0 op_sel_hi:[1,0]
	v_rcp_f32_e32 v166, v166
	v_rcp_f32_e32 v167, v167
	s_lshl_b64 s[52:53], s[90:91], 8
	v_mov_b32_e32 v168, v145
	v_mov_b32_e32 v164, v144
	v_pk_mul_f32 v[124:125], v[124:125], v[166:167]
	v_pk_mul_f32 v[166:167], v[126:127], v[244:245] op_sel_hi:[1,0]
	v_exp_f32_e32 v166, v166
	v_exp_f32_e32 v167, v167
	v_pk_mul_f32 v[120:121], v[120:121], v[124:125]
	s_add_u32 s52, s52, s31
	v_pk_add_f32 v[124:125], v[166:167], 1.0 op_sel_hi:[1,0]
	v_pk_mul_f32 v[166:167], v[116:117], v[244:245] op_sel_hi:[1,0]
	v_rcp_f32_e32 v124, v124
	v_rcp_f32_e32 v125, v125
	v_exp_f32_e32 v166, v166
	v_exp_f32_e32 v167, v167
	v_pk_mul_f32 v[124:125], v[126:127], v[124:125]
	v_pk_add_f32 v[126:127], v[166:167], 1.0 op_sel_hi:[1,0]
	v_pk_mul_f32 v[166:167], v[118:119], v[244:245] op_sel_hi:[1,0]
	v_exp_f32_e32 v166, v166
	v_exp_f32_e32 v167, v167
	v_rcp_f32_e32 v126, v126
	v_rcp_f32_e32 v127, v127
	v_pk_add_f32 v[166:167], v[166:167], 1.0 op_sel_hi:[1,0]
	v_rcp_f32_e32 v166, v166
	v_rcp_f32_e32 v167, v167
	v_pk_mul_f32 v[116:117], v[116:117], v[126:127]
	v_ashrrev_i32_e32 v165, 31, v164
	v_pk_mul_f32 v[112:113], v[112:113], v[116:117]
	v_pk_mul_f32 v[116:117], v[118:119], v[166:167]
	s_addc_u32 s53, s53, s34
	v_pk_mul_f32 v[122:123], v[122:123], v[124:125]
	v_pk_mul_f32 v[118:119], v[114:115], v[116:117]
	v_lshl_add_u64 v[124:125], s[52:53], 0, v[164:165]
	v_cvt_pk_bf16_f32 v116, v112, v113
	v_mov_b64_e32 v[112:113], s[64:65]
	v_cvt_pk_bf16_f32 v117, v118, v119
	v_mad_u64_u32 v[112:113], s[52:53], v124, s73, v[112:113]
	v_pk_mul_f32 v[118:119], v[108:109], v[244:245] op_sel_hi:[1,0]
	s_lshl_b32 s52, s81, 7
	v_exp_f32_e32 v118, v118
	v_exp_f32_e32 v119, v119
	v_mad_i32_i24 v113, v125, s73, v113
	s_ashr_i32 s53, s52, 31
	v_lshlrev_b32_e32 v168, 3, v168
	v_lshl_add_u64 v[112:113], s[52:53], 1, v[112:113]
	v_ashrrev_i32_e32 v169, 31, v168
	v_lshl_add_u64 v[112:113], v[112:113], 0, s[70:71]
	v_cvt_pk_bf16_f32 v114, v120, v121
	v_cvt_pk_bf16_f32 v115, v122, v123
	v_pk_add_f32 v[118:119], v[118:119], 1.0 op_sel_hi:[1,0]
	v_lshl_add_u64 v[112:113], v[168:169], 1, v[112:113]
	v_rcp_f32_e32 v118, v118
	v_rcp_f32_e32 v119, v119
	global_store_dwordx4 v[112:113], v[114:117], off
	s_mov_b32 s52, 0x16000
	v_pk_mul_f32 v[108:109], v[108:109], v[118:119]
	v_pk_mul_f32 v[114:115], v[110:111], v[244:245] op_sel_hi:[1,0]
	v_exp_f32_e32 v114, v114
	v_exp_f32_e32 v115, v115
	v_pk_mul_f32 v[104:105], v[104:105], v[108:109]
	v_pk_add_f32 v[108:109], v[114:115], 1.0 op_sel_hi:[1,0]
	v_pk_mul_f32 v[114:115], v[100:101], v[244:245] op_sel_hi:[1,0]
	v_rcp_f32_e32 v108, v108
	v_rcp_f32_e32 v109, v109
	v_exp_f32_e32 v114, v114
	v_exp_f32_e32 v115, v115
	v_pk_mul_f32 v[108:109], v[110:111], v[108:109]
	v_pk_add_f32 v[110:111], v[114:115], 1.0 op_sel_hi:[1,0]
	v_pk_mul_f32 v[114:115], v[102:103], v[244:245] op_sel_hi:[1,0]
	v_exp_f32_e32 v114, v114
	v_exp_f32_e32 v115, v115
	v_rcp_f32_e32 v110, v110
	v_rcp_f32_e32 v111, v111
	v_pk_add_f32 v[114:115], v[114:115], 1.0 op_sel_hi:[1,0]
	v_rcp_f32_e32 v114, v114
	v_rcp_f32_e32 v115, v115
	v_pk_mul_f32 v[100:101], v[100:101], v[110:111]
	v_pk_mul_f32 v[106:107], v[106:107], v[108:109]
	v_pk_mul_f32 v[100:101], v[96:97], v[100:101]
	v_pk_mul_f32 v[96:97], v[102:103], v[114:115]
	s_nop 0
	v_pk_mul_f32 v[102:103], v[98:99], v[96:97]
	v_mul_f32_e32 v99, 0xbfb8aa3b, v92
	v_cvt_pk_bf16_f32 v98, v100, v101
	v_exp_f32_e32 v100, v99
	v_mul_f32_e32 v99, 0xbfb8aa3b, v93
	v_exp_f32_e32 v101, v99
	v_cvt_pk_bf16_f32 v99, v102, v103
	v_add_co_u32_e32 v102, vcc, s52, v112
	v_cvt_pk_bf16_f32 v96, v104, v105
	v_cvt_pk_bf16_f32 v97, v106, v107
	v_pk_add_f32 v[100:101], v[100:101], 1.0 op_sel_hi:[1,0]
	v_addc_co_u32_e32 v103, vcc, 0, v113, vcc
	v_rcp_f32_e32 v100, v100
	v_rcp_f32_e32 v101, v101
	global_store_dwordx4 v[102:103], v[96:99], off
	s_mov_b32 s52, 0x2c000
	v_pk_mul_f32 v[92:93], v[92:93], v[100:101]
	v_pk_mul_f32 v[96:97], v[94:95], v[244:245] op_sel_hi:[1,0]
	v_exp_f32_e32 v96, v96
	v_exp_f32_e32 v97, v97
	v_pk_mul_f32 v[88:89], v[88:89], v[92:93]
	v_pk_add_f32 v[92:93], v[96:97], 1.0 op_sel_hi:[1,0]
	v_pk_mul_f32 v[96:97], v[84:85], v[244:245] op_sel_hi:[1,0]
	v_rcp_f32_e32 v92, v92
	v_rcp_f32_e32 v93, v93
	v_exp_f32_e32 v96, v96
	v_exp_f32_e32 v97, v97
	v_pk_mul_f32 v[92:93], v[94:95], v[92:93]
	v_pk_add_f32 v[94:95], v[96:97], 1.0 op_sel_hi:[1,0]
	v_pk_mul_f32 v[96:97], v[86:87], v[244:245] op_sel_hi:[1,0]
	v_exp_f32_e32 v96, v96
	v_exp_f32_e32 v97, v97
	v_rcp_f32_e32 v94, v94
	v_rcp_f32_e32 v95, v95
	v_pk_add_f32 v[96:97], v[96:97], 1.0 op_sel_hi:[1,0]
	v_rcp_f32_e32 v96, v96
	v_rcp_f32_e32 v97, v97
	v_pk_mul_f32 v[84:85], v[84:85], v[94:95]
	v_pk_mul_f32 v[90:91], v[90:91], v[92:93]
	v_pk_mul_f32 v[84:85], v[80:81], v[84:85]
	v_pk_mul_f32 v[80:81], v[86:87], v[96:97]
	s_nop 0
	v_pk_mul_f32 v[86:87], v[82:83], v[80:81]
	v_mul_f32_e32 v83, 0xbfb8aa3b, v76
	v_cvt_pk_bf16_f32 v82, v84, v85
	v_exp_f32_e32 v84, v83
	v_mul_f32_e32 v83, 0xbfb8aa3b, v77
	v_exp_f32_e32 v85, v83
	v_cvt_pk_bf16_f32 v83, v86, v87
	v_add_co_u32_e32 v86, vcc, s52, v112
	v_cvt_pk_bf16_f32 v80, v88, v89
	v_cvt_pk_bf16_f32 v81, v90, v91
	v_pk_add_f32 v[84:85], v[84:85], 1.0 op_sel_hi:[1,0]
	v_addc_co_u32_e32 v87, vcc, 0, v113, vcc
	v_rcp_f32_e32 v84, v84
	v_rcp_f32_e32 v85, v85
	global_store_dwordx4 v[86:87], v[80:83], off
	s_mov_b32 s52, 0x42000
	v_pk_mul_f32 v[76:77], v[76:77], v[84:85]
	v_pk_mul_f32 v[80:81], v[78:79], v[244:245] op_sel_hi:[1,0]
	v_exp_f32_e32 v80, v80
	v_exp_f32_e32 v81, v81
	v_pk_mul_f32 v[72:73], v[72:73], v[76:77]
	v_pk_add_f32 v[76:77], v[80:81], 1.0 op_sel_hi:[1,0]
	v_pk_mul_f32 v[80:81], v[68:69], v[244:245] op_sel_hi:[1,0]
	v_rcp_f32_e32 v76, v76
	v_rcp_f32_e32 v77, v77
	v_exp_f32_e32 v80, v80
	v_exp_f32_e32 v81, v81
	v_pk_mul_f32 v[76:77], v[78:79], v[76:77]
	v_pk_add_f32 v[78:79], v[80:81], 1.0 op_sel_hi:[1,0]
	v_pk_mul_f32 v[80:81], v[70:71], v[244:245] op_sel_hi:[1,0]
	v_exp_f32_e32 v80, v80
	v_exp_f32_e32 v81, v81
	v_rcp_f32_e32 v78, v78
	v_rcp_f32_e32 v79, v79
	v_pk_add_f32 v[80:81], v[80:81], 1.0 op_sel_hi:[1,0]
	v_rcp_f32_e32 v80, v80
	v_rcp_f32_e32 v81, v81
	v_pk_mul_f32 v[68:69], v[68:69], v[78:79]
	v_pk_mul_f32 v[74:75], v[74:75], v[76:77]
	v_pk_mul_f32 v[68:69], v[64:65], v[68:69]
	v_pk_mul_f32 v[64:65], v[70:71], v[80:81]
	s_nop 0
	v_pk_mul_f32 v[70:71], v[66:67], v[64:65]
	v_mul_f32_e32 v67, 0xbfb8aa3b, v60
	v_cvt_pk_bf16_f32 v66, v68, v69
	v_exp_f32_e32 v68, v67
	v_mul_f32_e32 v67, 0xbfb8aa3b, v61
	v_exp_f32_e32 v69, v67
	v_cvt_pk_bf16_f32 v67, v70, v71
	v_add_co_u32_e32 v70, vcc, s52, v112
	v_cvt_pk_bf16_f32 v64, v72, v73
	v_cvt_pk_bf16_f32 v65, v74, v75
	v_pk_add_f32 v[68:69], v[68:69], 1.0 op_sel_hi:[1,0]
	v_addc_co_u32_e32 v71, vcc, 0, v113, vcc
	v_rcp_f32_e32 v68, v68
	v_rcp_f32_e32 v69, v69
	global_store_dwordx4 v[70:71], v[64:67], off
	s_mov_b32 s52, 0xb0000
	v_pk_mul_f32 v[60:61], v[60:61], v[68:69]
	v_pk_mul_f32 v[64:65], v[62:63], v[244:245] op_sel_hi:[1,0]
	v_exp_f32_e32 v64, v64
	v_exp_f32_e32 v65, v65
	v_pk_mul_f32 v[56:57], v[56:57], v[60:61]
	v_pk_add_f32 v[60:61], v[64:65], 1.0 op_sel_hi:[1,0]
	v_pk_mul_f32 v[64:65], v[52:53], v[244:245] op_sel_hi:[1,0]
	v_rcp_f32_e32 v60, v60
	v_rcp_f32_e32 v61, v61
	v_exp_f32_e32 v64, v64
	v_exp_f32_e32 v65, v65
	v_pk_mul_f32 v[60:61], v[62:63], v[60:61]
	v_pk_add_f32 v[62:63], v[64:65], 1.0 op_sel_hi:[1,0]
	v_pk_mul_f32 v[64:65], v[54:55], v[244:245] op_sel_hi:[1,0]
	v_exp_f32_e32 v64, v64
	v_exp_f32_e32 v65, v65
	v_rcp_f32_e32 v62, v62
	v_rcp_f32_e32 v63, v63
	v_pk_add_f32 v[64:65], v[64:65], 1.0 op_sel_hi:[1,0]
	v_rcp_f32_e32 v64, v64
	v_rcp_f32_e32 v65, v65
	v_pk_mul_f32 v[52:53], v[52:53], v[62:63]
	v_pk_mul_f32 v[58:59], v[58:59], v[60:61]
	v_pk_mul_f32 v[52:53], v[48:49], v[52:53]
	v_pk_mul_f32 v[48:49], v[54:55], v[64:65]
	s_nop 0
	v_pk_mul_f32 v[54:55], v[50:51], v[48:49]
	v_mul_f32_e32 v51, 0xbfb8aa3b, v44
	v_cvt_pk_bf16_f32 v50, v52, v53
	v_exp_f32_e32 v52, v51
	v_mul_f32_e32 v51, 0xbfb8aa3b, v45
	v_exp_f32_e32 v53, v51
	v_cvt_pk_bf16_f32 v51, v54, v55
	v_add_co_u32_e32 v54, vcc, s52, v112
	v_cvt_pk_bf16_f32 v48, v56, v57
	v_cvt_pk_bf16_f32 v49, v58, v59
	v_pk_add_f32 v[52:53], v[52:53], 1.0 op_sel_hi:[1,0]
	v_addc_co_u32_e32 v55, vcc, 0, v113, vcc
	v_rcp_f32_e32 v52, v52
	v_rcp_f32_e32 v53, v53
	global_store_dwordx4 v[54:55], v[48:51], off
	s_mov_b32 s52, 0xc6000
	v_pk_mul_f32 v[44:45], v[44:45], v[52:53]
	v_pk_mul_f32 v[48:49], v[46:47], v[244:245] op_sel_hi:[1,0]
	v_exp_f32_e32 v48, v48
	v_exp_f32_e32 v49, v49
	v_pk_mul_f32 v[40:41], v[40:41], v[44:45]
	v_pk_add_f32 v[44:45], v[48:49], 1.0 op_sel_hi:[1,0]
	v_pk_mul_f32 v[48:49], v[36:37], v[244:245] op_sel_hi:[1,0]
	v_rcp_f32_e32 v44, v44
	v_rcp_f32_e32 v45, v45
	v_exp_f32_e32 v48, v48
	v_exp_f32_e32 v49, v49
	v_pk_mul_f32 v[44:45], v[46:47], v[44:45]
	v_pk_add_f32 v[46:47], v[48:49], 1.0 op_sel_hi:[1,0]
	v_pk_mul_f32 v[48:49], v[38:39], v[244:245] op_sel_hi:[1,0]
	v_exp_f32_e32 v48, v48
	v_exp_f32_e32 v49, v49
	v_rcp_f32_e32 v46, v46
	v_rcp_f32_e32 v47, v47
	v_pk_add_f32 v[48:49], v[48:49], 1.0 op_sel_hi:[1,0]
	v_rcp_f32_e32 v48, v48
	v_rcp_f32_e32 v49, v49
	v_pk_mul_f32 v[36:37], v[36:37], v[46:47]
	v_pk_mul_f32 v[42:43], v[42:43], v[44:45]
	v_pk_mul_f32 v[36:37], v[32:33], v[36:37]
	v_pk_mul_f32 v[32:33], v[38:39], v[48:49]
	s_nop 0
	v_pk_mul_f32 v[38:39], v[34:35], v[32:33]
	v_mul_f32_e32 v35, 0xbfb8aa3b, v28
	v_cvt_pk_bf16_f32 v34, v36, v37
	v_exp_f32_e32 v36, v35
	v_mul_f32_e32 v35, 0xbfb8aa3b, v29
	v_exp_f32_e32 v37, v35
	v_cvt_pk_bf16_f32 v35, v38, v39
	v_add_co_u32_e32 v38, vcc, s52, v112
	v_cvt_pk_bf16_f32 v32, v40, v41
	v_cvt_pk_bf16_f32 v33, v42, v43
	v_pk_add_f32 v[36:37], v[36:37], 1.0 op_sel_hi:[1,0]
	v_addc_co_u32_e32 v39, vcc, 0, v113, vcc
	v_rcp_f32_e32 v36, v36
	v_rcp_f32_e32 v37, v37
	global_store_dwordx4 v[38:39], v[32:35], off
	s_mov_b32 s52, 0xdc000
	v_pk_mul_f32 v[28:29], v[28:29], v[36:37]
	v_pk_mul_f32 v[32:33], v[30:31], v[244:245] op_sel_hi:[1,0]
	v_exp_f32_e32 v32, v32
	v_exp_f32_e32 v33, v33
	v_pk_mul_f32 v[24:25], v[24:25], v[28:29]
	v_pk_add_f32 v[28:29], v[32:33], 1.0 op_sel_hi:[1,0]
	v_pk_mul_f32 v[32:33], v[20:21], v[244:245] op_sel_hi:[1,0]
	v_rcp_f32_e32 v28, v28
	v_rcp_f32_e32 v29, v29
	v_exp_f32_e32 v32, v32
	v_exp_f32_e32 v33, v33
	v_pk_mul_f32 v[28:29], v[30:31], v[28:29]
	v_pk_add_f32 v[30:31], v[32:33], 1.0 op_sel_hi:[1,0]
	v_pk_mul_f32 v[32:33], v[22:23], v[244:245] op_sel_hi:[1,0]
	v_exp_f32_e32 v32, v32
	v_exp_f32_e32 v33, v33
	v_rcp_f32_e32 v30, v30
	v_rcp_f32_e32 v31, v31
	v_pk_add_f32 v[32:33], v[32:33], 1.0 op_sel_hi:[1,0]
	v_rcp_f32_e32 v32, v32
	v_rcp_f32_e32 v33, v33
	v_pk_mul_f32 v[20:21], v[20:21], v[30:31]
	v_pk_mul_f32 v[26:27], v[26:27], v[28:29]
	v_pk_mul_f32 v[20:21], v[16:17], v[20:21]
	v_pk_mul_f32 v[16:17], v[22:23], v[32:33]
	s_nop 0
	v_pk_mul_f32 v[22:23], v[18:19], v[16:17]
	v_mul_f32_e32 v19, 0xbfb8aa3b, v12
	v_cvt_pk_bf16_f32 v18, v20, v21
	v_exp_f32_e32 v20, v19
	v_mul_f32_e32 v19, 0xbfb8aa3b, v13
	v_exp_f32_e32 v21, v19
	v_cvt_pk_bf16_f32 v19, v22, v23
	v_add_co_u32_e32 v22, vcc, s52, v112
	v_cvt_pk_bf16_f32 v16, v24, v25
	v_cvt_pk_bf16_f32 v17, v26, v27
	v_pk_add_f32 v[20:21], v[20:21], 1.0 op_sel_hi:[1,0]
	v_addc_co_u32_e32 v23, vcc, 0, v113, vcc
	v_rcp_f32_e32 v20, v20
	v_rcp_f32_e32 v21, v21
	global_store_dwordx4 v[22:23], v[16:19], off
	v_pk_mul_f32 v[12:13], v[12:13], v[20:21]
	s_nop 0
	v_pk_mul_f32 v[16:17], v[14:15], v[244:245] op_sel_hi:[1,0]
	v_exp_f32_e32 v16, v16
	v_exp_f32_e32 v17, v17
	v_pk_mul_f32 v[8:9], v[8:9], v[12:13]
	v_pk_add_f32 v[12:13], v[16:17], 1.0 op_sel_hi:[1,0]
	v_pk_mul_f32 v[16:17], v[4:5], v[244:245] op_sel_hi:[1,0]
	v_rcp_f32_e32 v12, v12
	v_rcp_f32_e32 v13, v13
	v_exp_f32_e32 v16, v16
	v_exp_f32_e32 v17, v17
	v_pk_mul_f32 v[12:13], v[14:15], v[12:13]
	v_pk_add_f32 v[14:15], v[16:17], 1.0 op_sel_hi:[1,0]
	v_pk_mul_f32 v[16:17], v[6:7], v[244:245] op_sel_hi:[1,0]
	v_exp_f32_e32 v16, v16
	v_exp_f32_e32 v17, v17
	v_rcp_f32_e32 v14, v14
	v_rcp_f32_e32 v15, v15
	v_pk_add_f32 v[16:17], v[16:17], 1.0 op_sel_hi:[1,0]
	v_rcp_f32_e32 v16, v16
	v_rcp_f32_e32 v17, v17
	v_pk_mul_f32 v[4:5], v[4:5], v[14:15]
	v_pk_mul_f32 v[10:11], v[10:11], v[12:13]
	v_pk_mul_f32 v[4:5], v[0:1], v[4:5]
	v_pk_mul_f32 v[0:1], v[6:7], v[16:17]
	s_nop 0
	v_pk_mul_f32 v[6:7], v[2:3], v[0:1]
	v_cvt_pk_bf16_f32 v2, v4, v5
	v_add_co_u32_e32 v4, vcc, 0xf2000, v112
	v_cvt_pk_bf16_f32 v0, v8, v9
	s_nop 0
	v_addc_co_u32_e32 v5, vcc, 0, v113, vcc
	v_cvt_pk_bf16_f32 v1, v10, v11
	v_cvt_pk_bf16_f32 v3, v6, v7
	s_and_b64 vcc, exec, s[4:5]
	s_mov_b64 s[4:5], -1
	global_store_dwordx4 v[4:5], v[0:3], off
	s_cbranch_vccnz .LBB0_426
	s_andn2_b64 vcc, exec, s[74:75]
	s_cbranch_vccnz .LBB0_425
	s_barrier
	s_branch .LBB0_425

.LBB0_1752:
	v_pk_mul_f32 v[168:169], v[124:125], v[244:245] op_sel_hi:[1,0]
	v_exp_f32_e32 v168, v168
	v_exp_f32_e32 v169, v169
	v_mov_b32_e32 v166, v144
	v_pk_add_f32 v[168:169], v[168:169], 1.0 op_sel_hi:[1,0]
	v_rcp_f32_e32 v168, v168
	v_rcp_f32_e32 v169, v169
	v_mov_b32_e32 v165, v145
	s_ashr_i32 s43, s42, 31
	v_lshlrev_b32_e32 v170, 3, v165
	v_pk_mul_f32 v[124:125], v[124:125], v[168:169]
	v_mul_f32_e32 v165, 0xbfb8aa3b, v126
	v_mul_f32_e32 v168, 0xbfb8aa3b, v127
	v_exp_f32_e32 v165, v165
	v_exp_f32_e32 v168, v168
	v_pk_mul_f32 v[120:121], v[120:121], v[124:125]
	s_lshl_b64 s[42:43], s[42:43], 8
	v_add_f32_e32 v124, 1.0, v165
	v_add_f32_e32 v125, 1.0, v168
	v_mul_f32_e32 v165, 0xbfb8aa3b, v116
	v_rcp_f32_e32 v124, v124
	v_rcp_f32_e32 v125, v125
	v_exp_f32_e32 v165, v165
	v_mul_f32_e32 v168, 0xbfb8aa3b, v117
	v_exp_f32_e32 v168, v168
	v_pk_mul_f32 v[124:125], v[126:127], v[124:125]
	v_add_f32_e32 v126, 1.0, v165
	v_mul_f32_e32 v165, 0xbfb8aa3b, v118
	v_add_f32_e32 v127, 1.0, v168
	v_exp_f32_e32 v165, v165
	v_mul_f32_e32 v168, 0xbfb8aa3b, v119
	v_exp_f32_e32 v169, v168
	v_rcp_f32_e32 v126, v126
	v_add_f32_e32 v165, 1.0, v165
	v_rcp_f32_e32 v127, v127
	v_rcp_f32_e32 v168, v165
	v_add_f32_e32 v165, 1.0, v169
	v_rcp_f32_e32 v169, v165
	v_pk_mul_f32 v[116:117], v[116:117], v[126:127]
	s_add_u32 s42, s42, s92
	v_ashrrev_i32_e32 v167, 31, v166
	v_pk_mul_f32 v[112:113], v[112:113], v[116:117]
	v_pk_mul_f32 v[116:117], v[118:119], v[168:169]
	s_addc_u32 s43, s43, s97
	v_pk_mul_f32 v[122:123], v[122:123], v[124:125]
	v_pk_mul_f32 v[118:119], v[114:115], v[116:117]
	v_lshl_add_u64 v[124:125], s[42:43], 0, v[166:167]
	v_cvt_pk_bf16_f32 v116, v112, v113
	v_mov_b64_e32 v[112:113], s[64:65]
	v_cvt_pk_bf16_f32 v117, v118, v119
	v_mad_u64_u32 v[112:113], s[42:43], v124, s69, v[112:113]
	v_pk_mul_f32 v[118:119], v[108:109], v[244:245] op_sel_hi:[1,0]
	s_lshl_b32 s42, s78, 7
	v_exp_f32_e32 v118, v118
	v_exp_f32_e32 v119, v119
	v_mad_i32_i24 v113, v125, s69, v113
	s_ashr_i32 s43, s42, 31
	v_lshl_add_u64 v[112:113], s[42:43], 1, v[112:113]
	v_ashrrev_i32_e32 v171, 31, v170
	v_lshl_add_u64 v[112:113], v[112:113], 0, s[16:17]
	v_cvt_pk_bf16_f32 v114, v120, v121
	v_cvt_pk_bf16_f32 v115, v122, v123
	v_pk_add_f32 v[118:119], v[118:119], 1.0 op_sel_hi:[1,0]
	v_lshl_add_u64 v[112:113], v[170:171], 1, v[112:113]
	v_rcp_f32_e32 v118, v118
	v_rcp_f32_e32 v119, v119
	global_store_dwordx4 v[112:113], v[114:117], off
	v_pk_mul_f32 v[108:109], v[108:109], v[118:119]
	s_nop 0
	v_pk_mul_f32 v[114:115], v[110:111], v[244:245] op_sel_hi:[1,0]
	v_exp_f32_e32 v114, v114
	v_exp_f32_e32 v115, v115
	v_pk_mul_f32 v[104:105], v[104:105], v[108:109]
	v_pk_add_f32 v[108:109], v[114:115], 1.0 op_sel_hi:[1,0]
	v_pk_mul_f32 v[114:115], v[100:101], v[244:245] op_sel_hi:[1,0]
	v_rcp_f32_e32 v108, v108
	v_rcp_f32_e32 v109, v109
	v_exp_f32_e32 v114, v114
	v_exp_f32_e32 v115, v115
	v_pk_mul_f32 v[108:109], v[110:111], v[108:109]
	v_pk_add_f32 v[110:111], v[114:115], 1.0 op_sel_hi:[1,0]
	v_pk_mul_f32 v[114:115], v[102:103], v[244:245] op_sel_hi:[1,0]
	v_exp_f32_e32 v114, v114
	v_exp_f32_e32 v115, v115
	v_rcp_f32_e32 v110, v110
	v_rcp_f32_e32 v111, v111
	v_pk_add_f32 v[114:115], v[114:115], 1.0 op_sel_hi:[1,0]
	v_rcp_f32_e32 v114, v114
	v_rcp_f32_e32 v115, v115
	v_pk_mul_f32 v[100:101], v[100:101], v[110:111]
	v_pk_mul_f32 v[106:107], v[106:107], v[108:109]
	v_pk_mul_f32 v[100:101], v[96:97], v[100:101]
	v_pk_mul_f32 v[96:97], v[102:103], v[114:115]
	s_nop 0
	v_pk_mul_f32 v[102:103], v[98:99], v[96:97]
	v_mul_f32_e32 v99, 0xbfb8aa3b, v92
	v_cvt_pk_bf16_f32 v98, v100, v101
	v_exp_f32_e32 v100, v99
	v_mul_f32_e32 v99, 0xbfb8aa3b, v93
	v_exp_f32_e32 v101, v99
	v_cvt_pk_bf16_f32 v99, v102, v103
	v_add_co_u32_e32 v102, vcc, s50, v112
	v_cvt_pk_bf16_f32 v96, v104, v105
	v_cvt_pk_bf16_f32 v97, v106, v107
	v_pk_add_f32 v[100:101], v[100:101], 1.0 op_sel_hi:[1,0]
	v_addc_co_u32_e32 v103, vcc, 0, v113, vcc
	v_rcp_f32_e32 v100, v100
	v_rcp_f32_e32 v101, v101
	global_store_dwordx4 v[102:103], v[96:99], off
	v_pk_mul_f32 v[92:93], v[92:93], v[100:101]
	s_nop 0
	v_pk_mul_f32 v[96:97], v[94:95], v[244:245] op_sel_hi:[1,0]
	v_exp_f32_e32 v96, v96
	v_exp_f32_e32 v97, v97
	v_pk_mul_f32 v[88:89], v[88:89], v[92:93]
	v_pk_add_f32 v[92:93], v[96:97], 1.0 op_sel_hi:[1,0]
	v_pk_mul_f32 v[96:97], v[84:85], v[244:245] op_sel_hi:[1,0]
	v_rcp_f32_e32 v92, v92
	v_rcp_f32_e32 v93, v93
	v_exp_f32_e32 v96, v96
	v_exp_f32_e32 v97, v97
	v_pk_mul_f32 v[92:93], v[94:95], v[92:93]
	v_pk_add_f32 v[94:95], v[96:97], 1.0 op_sel_hi:[1,0]
	v_pk_mul_f32 v[96:97], v[86:87], v[244:245] op_sel_hi:[1,0]
	v_exp_f32_e32 v96, v96
	v_exp_f32_e32 v97, v97
	v_rcp_f32_e32 v94, v94
	v_rcp_f32_e32 v95, v95
	v_pk_add_f32 v[96:97], v[96:97], 1.0 op_sel_hi:[1,0]
	v_rcp_f32_e32 v96, v96
	v_rcp_f32_e32 v97, v97
	v_pk_mul_f32 v[84:85], v[84:85], v[94:95]
	v_pk_mul_f32 v[90:91], v[90:91], v[92:93]
	v_pk_mul_f32 v[84:85], v[80:81], v[84:85]
	v_pk_mul_f32 v[80:81], v[86:87], v[96:97]
	s_nop 0
	v_pk_mul_f32 v[86:87], v[82:83], v[80:81]
	v_mul_f32_e32 v83, 0xbfb8aa3b, v76
	v_cvt_pk_bf16_f32 v82, v84, v85
	v_exp_f32_e32 v84, v83
	v_mul_f32_e32 v83, 0xbfb8aa3b, v77
	v_exp_f32_e32 v85, v83
	v_cvt_pk_bf16_f32 v83, v86, v87
	v_add_co_u32_e32 v86, vcc, s70, v112
	v_cvt_pk_bf16_f32 v80, v88, v89
	v_cvt_pk_bf16_f32 v81, v90, v91
	v_pk_add_f32 v[84:85], v[84:85], 1.0 op_sel_hi:[1,0]
	v_addc_co_u32_e32 v87, vcc, 0, v113, vcc
	v_rcp_f32_e32 v84, v84
	v_rcp_f32_e32 v85, v85
	global_store_dwordx4 v[86:87], v[80:83], off
	v_pk_mul_f32 v[76:77], v[76:77], v[84:85]
	s_nop 0
	v_pk_mul_f32 v[80:81], v[78:79], v[244:245] op_sel_hi:[1,0]
	v_exp_f32_e32 v80, v80
	v_exp_f32_e32 v81, v81
	v_pk_mul_f32 v[72:73], v[72:73], v[76:77]
	v_pk_add_f32 v[76:77], v[80:81], 1.0 op_sel_hi:[1,0]
	v_pk_mul_f32 v[80:81], v[68:69], v[244:245] op_sel_hi:[1,0]
	v_rcp_f32_e32 v76, v76
	v_rcp_f32_e32 v77, v77
	v_exp_f32_e32 v80, v80
	v_exp_f32_e32 v81, v81
	v_pk_mul_f32 v[76:77], v[78:79], v[76:77]
	v_pk_add_f32 v[78:79], v[80:81], 1.0 op_sel_hi:[1,0]
	v_pk_mul_f32 v[80:81], v[70:71], v[244:245] op_sel_hi:[1,0]
	v_exp_f32_e32 v80, v80
	v_exp_f32_e32 v81, v81
	v_rcp_f32_e32 v78, v78
	v_rcp_f32_e32 v79, v79
	v_pk_add_f32 v[80:81], v[80:81], 1.0 op_sel_hi:[1,0]
	v_rcp_f32_e32 v80, v80
	v_rcp_f32_e32 v81, v81
	v_pk_mul_f32 v[68:69], v[68:69], v[78:79]
	v_pk_mul_f32 v[74:75], v[74:75], v[76:77]
	v_pk_mul_f32 v[68:69], v[64:65], v[68:69]
	v_pk_mul_f32 v[64:65], v[70:71], v[80:81]
	s_nop 0
	v_pk_mul_f32 v[70:71], v[66:67], v[64:65]
	v_mul_f32_e32 v67, 0xbfb8aa3b, v60
	v_cvt_pk_bf16_f32 v66, v68, v69
	v_exp_f32_e32 v68, v67
	v_mul_f32_e32 v67, 0xbfb8aa3b, v61
	v_exp_f32_e32 v69, v67
	v_cvt_pk_bf16_f32 v67, v70, v71
	v_add_co_u32_e32 v70, vcc, s71, v112
	v_cvt_pk_bf16_f32 v64, v72, v73
	v_cvt_pk_bf16_f32 v65, v74, v75
	v_pk_add_f32 v[68:69], v[68:69], 1.0 op_sel_hi:[1,0]
	v_addc_co_u32_e32 v71, vcc, 0, v113, vcc
	v_rcp_f32_e32 v68, v68
	v_rcp_f32_e32 v69, v69
	global_store_dwordx4 v[70:71], v[64:67], off
	v_pk_mul_f32 v[60:61], v[60:61], v[68:69]
	s_nop 0
	v_pk_mul_f32 v[64:65], v[62:63], v[244:245] op_sel_hi:[1,0]
	v_exp_f32_e32 v64, v64
	v_exp_f32_e32 v65, v65
	v_pk_mul_f32 v[56:57], v[56:57], v[60:61]
	v_pk_add_f32 v[60:61], v[64:65], 1.0 op_sel_hi:[1,0]
	v_pk_mul_f32 v[64:65], v[52:53], v[244:245] op_sel_hi:[1,0]
	v_rcp_f32_e32 v60, v60
	v_rcp_f32_e32 v61, v61
	v_exp_f32_e32 v64, v64
	v_exp_f32_e32 v65, v65
	v_pk_mul_f32 v[60:61], v[62:63], v[60:61]
	v_pk_add_f32 v[62:63], v[64:65], 1.0 op_sel_hi:[1,0]
	v_pk_mul_f32 v[64:65], v[54:55], v[244:245] op_sel_hi:[1,0]
	v_exp_f32_e32 v64, v64
	v_exp_f32_e32 v65, v65
	v_rcp_f32_e32 v62, v62
	v_rcp_f32_e32 v63, v63
	v_pk_add_f32 v[64:65], v[64:65], 1.0 op_sel_hi:[1,0]
	v_rcp_f32_e32 v64, v64
	v_rcp_f32_e32 v65, v65
	v_pk_mul_f32 v[52:53], v[52:53], v[62:63]
	v_pk_mul_f32 v[58:59], v[58:59], v[60:61]
	v_pk_mul_f32 v[52:53], v[48:49], v[52:53]
	v_pk_mul_f32 v[48:49], v[54:55], v[64:65]
	s_nop 0
	v_pk_mul_f32 v[54:55], v[50:51], v[48:49]
	v_mul_f32_e32 v51, 0xbfb8aa3b, v44
	v_cvt_pk_bf16_f32 v50, v52, v53
	v_exp_f32_e32 v52, v51
	v_mul_f32_e32 v51, 0xbfb8aa3b, v45
	v_exp_f32_e32 v53, v51
	v_cvt_pk_bf16_f32 v51, v54, v55
	v_add_co_u32_e32 v54, vcc, s72, v112
	v_cvt_pk_bf16_f32 v48, v56, v57
	v_cvt_pk_bf16_f32 v49, v58, v59
	v_pk_add_f32 v[52:53], v[52:53], 1.0 op_sel_hi:[1,0]
	v_addc_co_u32_e32 v55, vcc, 0, v113, vcc
	v_rcp_f32_e32 v52, v52
	v_rcp_f32_e32 v53, v53
	global_store_dwordx4 v[54:55], v[48:51], off
	v_pk_mul_f32 v[44:45], v[44:45], v[52:53]
	s_nop 0
	v_pk_mul_f32 v[48:49], v[46:47], v[244:245] op_sel_hi:[1,0]
	v_exp_f32_e32 v48, v48
	v_exp_f32_e32 v49, v49
	v_pk_mul_f32 v[40:41], v[40:41], v[44:45]
	v_pk_add_f32 v[44:45], v[48:49], 1.0 op_sel_hi:[1,0]
	v_pk_mul_f32 v[48:49], v[36:37], v[244:245] op_sel_hi:[1,0]
	v_rcp_f32_e32 v44, v44
	v_rcp_f32_e32 v45, v45
	v_exp_f32_e32 v48, v48
	v_exp_f32_e32 v49, v49
	v_pk_mul_f32 v[44:45], v[46:47], v[44:45]
	v_pk_add_f32 v[46:47], v[48:49], 1.0 op_sel_hi:[1,0]
	v_pk_mul_f32 v[48:49], v[38:39], v[244:245] op_sel_hi:[1,0]
	v_exp_f32_e32 v48, v48
	v_exp_f32_e32 v49, v49
	v_rcp_f32_e32 v46, v46
	v_rcp_f32_e32 v47, v47
	v_pk_add_f32 v[48:49], v[48:49], 1.0 op_sel_hi:[1,0]
	v_rcp_f32_e32 v48, v48
	v_rcp_f32_e32 v49, v49
	v_pk_mul_f32 v[36:37], v[36:37], v[46:47]
	v_pk_mul_f32 v[42:43], v[42:43], v[44:45]
	v_pk_mul_f32 v[36:37], v[32:33], v[36:37]
	v_pk_mul_f32 v[32:33], v[38:39], v[48:49]
	s_nop 0
	v_pk_mul_f32 v[38:39], v[34:35], v[32:33]
	v_mul_f32_e32 v35, 0xbfb8aa3b, v28
	v_cvt_pk_bf16_f32 v34, v36, v37
	v_exp_f32_e32 v36, v35
	v_mul_f32_e32 v35, 0xbfb8aa3b, v29
	v_exp_f32_e32 v37, v35
	v_cvt_pk_bf16_f32 v35, v38, v39
	v_add_co_u32_e32 v38, vcc, s73, v112
	v_cvt_pk_bf16_f32 v32, v40, v41
	v_cvt_pk_bf16_f32 v33, v42, v43
	v_pk_add_f32 v[36:37], v[36:37], 1.0 op_sel_hi:[1,0]
	v_addc_co_u32_e32 v39, vcc, 0, v113, vcc
	v_rcp_f32_e32 v36, v36
	v_rcp_f32_e32 v37, v37
	global_store_dwordx4 v[38:39], v[32:35], off
	v_pk_mul_f32 v[28:29], v[28:29], v[36:37]
	s_nop 0
	v_pk_mul_f32 v[32:33], v[30:31], v[244:245] op_sel_hi:[1,0]
	v_exp_f32_e32 v32, v32
	v_exp_f32_e32 v33, v33
	v_pk_mul_f32 v[24:25], v[24:25], v[28:29]
	v_pk_add_f32 v[28:29], v[32:33], 1.0 op_sel_hi:[1,0]
	v_pk_mul_f32 v[32:33], v[20:21], v[244:245] op_sel_hi:[1,0]
	v_rcp_f32_e32 v28, v28
	v_rcp_f32_e32 v29, v29
	v_exp_f32_e32 v32, v32
	v_exp_f32_e32 v33, v33
	v_pk_mul_f32 v[28:29], v[30:31], v[28:29]
	v_pk_add_f32 v[30:31], v[32:33], 1.0 op_sel_hi:[1,0]
	v_pk_mul_f32 v[32:33], v[22:23], v[244:245] op_sel_hi:[1,0]
	v_exp_f32_e32 v32, v32
	v_exp_f32_e32 v33, v33
	v_rcp_f32_e32 v30, v30
	v_rcp_f32_e32 v31, v31
	v_pk_add_f32 v[32:33], v[32:33], 1.0 op_sel_hi:[1,0]
	v_rcp_f32_e32 v32, v32
	v_rcp_f32_e32 v33, v33
	v_pk_mul_f32 v[20:21], v[20:21], v[30:31]
	v_pk_mul_f32 v[26:27], v[26:27], v[28:29]
	v_pk_mul_f32 v[20:21], v[16:17], v[20:21]
	v_pk_mul_f32 v[16:17], v[22:23], v[32:33]
	s_nop 0
	v_pk_mul_f32 v[22:23], v[18:19], v[16:17]
	v_mul_f32_e32 v19, 0xbfb8aa3b, v12
	v_cvt_pk_bf16_f32 v18, v20, v21
	v_exp_f32_e32 v20, v19
	v_mul_f32_e32 v19, 0xbfb8aa3b, v13
	v_exp_f32_e32 v21, v19
	v_cvt_pk_bf16_f32 v19, v22, v23
	v_add_co_u32_e32 v22, vcc, s74, v112
	v_cvt_pk_bf16_f32 v16, v24, v25
	v_cvt_pk_bf16_f32 v17, v26, v27
	v_pk_add_f32 v[20:21], v[20:21], 1.0 op_sel_hi:[1,0]
	v_addc_co_u32_e32 v23, vcc, 0, v113, vcc
	v_rcp_f32_e32 v20, v20
	v_rcp_f32_e32 v21, v21
	global_store_dwordx4 v[22:23], v[16:19], off
	v_pk_mul_f32 v[12:13], v[12:13], v[20:21]
	s_nop 0
	v_pk_mul_f32 v[16:17], v[14:15], v[244:245] op_sel_hi:[1,0]
	v_exp_f32_e32 v16, v16
	v_exp_f32_e32 v17, v17
	v_pk_mul_f32 v[8:9], v[8:9], v[12:13]
	v_pk_add_f32 v[12:13], v[16:17], 1.0 op_sel_hi:[1,0]
	v_pk_mul_f32 v[16:17], v[4:5], v[244:245] op_sel_hi:[1,0]
	v_rcp_f32_e32 v12, v12
	v_rcp_f32_e32 v13, v13
	v_exp_f32_e32 v16, v16
	v_exp_f32_e32 v17, v17
	v_pk_mul_f32 v[12:13], v[14:15], v[12:13]
	v_pk_add_f32 v[14:15], v[16:17], 1.0 op_sel_hi:[1,0]
	v_pk_mul_f32 v[16:17], v[6:7], v[244:245] op_sel_hi:[1,0]
	v_exp_f32_e32 v16, v16
	v_exp_f32_e32 v17, v17
	v_rcp_f32_e32 v14, v14
	v_rcp_f32_e32 v15, v15
	v_pk_add_f32 v[16:17], v[16:17], 1.0 op_sel_hi:[1,0]
	v_rcp_f32_e32 v16, v16
	v_rcp_f32_e32 v17, v17
	v_pk_mul_f32 v[4:5], v[4:5], v[14:15]
	v_pk_mul_f32 v[10:11], v[10:11], v[12:13]
	v_pk_mul_f32 v[4:5], v[0:1], v[4:5]
	v_pk_mul_f32 v[0:1], v[6:7], v[16:17]
	s_nop 0
	v_pk_mul_f32 v[6:7], v[2:3], v[0:1]
	v_cvt_pk_bf16_f32 v2, v4, v5
	v_add_co_u32_e32 v4, vcc, 0xf2000, v112
	v_cvt_pk_bf16_f32 v0, v8, v9
	s_nop 0
	v_addc_co_u32_e32 v5, vcc, 0, v113, vcc
	v_cvt_pk_bf16_f32 v1, v10, v11
	v_cvt_pk_bf16_f32 v3, v6, v7
	s_and_b64 vcc, exec, s[6:7]
	s_mov_b64 s[6:7], -1
	global_store_dwordx4 v[4:5], v[0:3], off
	s_cbranch_vccnz .LBB0_1740
	s_andn2_b64 vcc, exec, s[18:19]
	s_cbranch_vccnz .LBB0_1739
	s_barrier
	s_branch .LBB0_1739
